# early conversion limited to the first 4480 in-proj weight tiles (fits under the compress-GEMM's shadow in phase 3), remaining tiles stay in the prologue phase
# baseline (speedup 1.0000x reference)
; __device__ __forceinline__ void prologue(LAS unsigned char* lds, const Ctx& P, int l) {
;     ...
;     for (int t = blockIdx.x; t < T_ALL; t += G) {
;         int q = t;
;         if (q < T_IN) { const int kt = q & 31, ntl = q >> 5; tconv_tile(tile, P.in[3] + (size_t)l * DM * INW, INW, kt * 64, ntl * 64, 1, (bf16_t*)(ws + WS_WIN), DM); continue; }
.Lp3_tc_go:
	v_mov_b32_e32 v26, 0x23f00
	ds_read_b64 v[34:35], v26 offset:24
	ds_read_b64 v[36:37], v26 offset:184
	ds_read_b64 v[38:39], v26 offset:192
	ds_read_b64 v[40:41], v26 offset:176
	ds_read_b64 v[42:43], v26 offset:136
	ds_read_b64 v[44:45], v26 offset:144
	ds_read_b64 v[46:47], v26 offset:80
	ds_read_b64 v[48:49], v26 offset:96
	s_waitcnt lgkmcnt(0)
	v_readfirstlane_b32 s4, v34
	v_readfirstlane_b32 s5, v35
	v_readfirstlane_b32 s6, v36
	v_readfirstlane_b32 s7, v37
	v_readfirstlane_b32 s8, v38
	v_readfirstlane_b32 s9, v39
	v_readfirstlane_b32 s10, v40
	v_readfirstlane_b32 s11, v41
	v_readfirstlane_b32 s12, v42
	v_readfirstlane_b32 s13, v43
	v_readfirstlane_b32 s14, v44
	v_readfirstlane_b32 s15, v45
	v_readfirstlane_b32 s16, v46
	v_readfirstlane_b32 s17, v47
	v_readfirstlane_b32 s18, v48
	v_readfirstlane_b32 s19, v49
	s_nop 3
	s_add_u32 s4, s4, 0x9460000
	s_addc_u32 s5, s5, 0
	s_add_u32 s6, s6, 0x2000000
	s_addc_u32 s7, s7, 0
	s_add_u32 s8, s8, 0x1000000
	s_addc_u32 s9, s9, 0
	s_add_u32 s10, s10, 0x1000000
	s_addc_u32 s11, s11, 0
	s_add_u32 s12, s12, 0x200000
	s_addc_u32 s13, s13, 0
	s_add_u32 s14, s14, 0x200000
	s_addc_u32 s15, s15, 0
	s_add_u32 s16, s16, 0x80000
	s_addc_u32 s17, s17, 0
	s_add_u32 s18, s18, 0x80000
	s_addc_u32 s19, s19, 0
	v_lshrrev_b32_e32 v20, 4, v234
	v_and_b32_e32 v21, 15, v234
	v_lshlrev_b32_e32 v21, 2, v21
	v_mul_u32_u24_e32 v22, 0x104, v20
	v_lshl_add_u32 v22, v21, 2, v22
	v_lshrrev_b32_e32 v24, 3, v234
	v_and_b32_e32 v25, 7, v234
	v_lshlrev_b32_e32 v25, 3, v25
	v_mul_u32_u24_e32 v23, 0x104, v25
	v_lshl_add_u32 v23, v24, 2, v23
	s_sub_u32 s24, s2, 32
	s_mov_b32 s25, s24
	s_min_u32 s0, s24, 4479
	s_mov_b32 s21, s0
	s_mov_b32 s0, s21
	s_cmpk_lt_u32 s0, 9600
	s_cbranch_scc0 .Ltc2_c2
	s_and_b32 s1, s0, 31
	s_lshl_b32 s1, s1, 6
	s_lshr_b32 s21, s0, 5
	s_lshl_b32 s21, s21, 6
	s_movk_i32 s29, 64
	s_cmpk_lt_u32 s21, 7680
	s_cbranch_scc1 .Ltc2_n4
	s_cmpk_lt_u32 s21, 18944
	s_cbranch_scc0 .Ltc2_t3
	s_add_u32 s21, s21, 48
	s_branch .Ltc2_n4

; __device__ __forceinline__ void tconv_tile(LAS float* tile, const float* src, int ld, int k0, int n0, int mode, bf16_t* dst, int K) {
;     ...
;     for (int it = 0; it < 2; ++it) { const int idx = tid + it * 512, kk = idx >> 4, n4 = (idx & 15) * 4, nn = n0 + n4; int oc = nn; bool valid = true;
;         if (mode == 1) { if (nn < 7680) oc = nn; else if (nn < 18944) oc = nn + 48; else if (nn < INW) oc = 7680 + (nn - 18944); else valid = false; }
;         f32x4 v = (f32x4){0.f, 0.f, 0.f, 0.f}; if (valid) v = *(const f32x4*)(src + (size_t)(k0 + kk) * ld + oc);
;         tile[kk * 65 + n4 + 0] = v[0]; tile[kk * 65 + n4 + 1] = v[1]; tile[kk * 65 + n4 + 2] = v[2]; tile[kk * 65 + n4 + 3] = v[3]; }
.Ltc2_d1:
	v_mov_b32_e32 v34, 0
	v_mov_b32_e32 v35, 0
	v_mov_b32_e32 v36, 0
	v_mov_b32_e32 v37, 0
	v_mov_b32_e32 v38, 0
	v_mov_b32_e32 v39, 0
	v_mov_b32_e32 v40, 0
	v_mov_b32_e32 v41, 0
	v_mul_u32_u24_e32 v26, s28, v20
	v_add_lshl_u32 v26, v26, v21, 2
	s_lshl_b32 s0, s28, 7
	v_add_u32_e32 v27, s0, v26
	v_cmp_gt_i32_e32 vcc, s29, v21
	s_and_saveexec_b64 s[0:1], vcc
	global_load_dwordx4 v[34:37], v26, s[26:27]
	global_load_dwordx4 v[38:41], v27, s[26:27]
	s_mov_b64 exec, s[0:1]
	s_add_u32 s24, s24, 0xe0
	s_min_u32 s0, s24, 4479
	s_mov_b32 s21, s0
	s_mov_b32 s0, s21
	s_cmpk_lt_u32 s0, 9600
	s_cbranch_scc0 .Ltc2_c15
	s_and_b32 s1, s0, 31
	s_lshl_b32 s1, s1, 6
	s_lshr_b32 s21, s0, 5
	s_lshl_b32 s21, s21, 6
	s_movk_i32 s29, 64
	s_cmpk_lt_u32 s21, 7680
	s_cbranch_scc1 .Ltc2_n17
	s_cmpk_lt_u32 s21, 18944
	s_cbranch_scc0 .Ltc2_t16
	s_add_u32 s21, s21, 48
	s_branch .Ltc2_n17

; __device__ __forceinline__ void tconv_tile(LAS float* tile, const float* src, int ld, int k0, int n0, int mode, bf16_t* dst, int K) {
;     ...
;     for (int it = 0; it < 2; ++it) { const int idx = tid + it * 512, kk = idx >> 4, n4 = (idx & 15) * 4, nn = n0 + n4; int oc = nn; bool valid = true;
;         if (mode == 1) { if (nn < 7680) oc = nn; else if (nn < 18944) oc = nn + 48; else if (nn < INW) oc = 7680 + (nn - 18944); else valid = false; }
;         f32x4 v = (f32x4){0.f, 0.f, 0.f, 0.f}; if (valid) v = *(const f32x4*)(src + (size_t)(k0 + kk) * ld + oc);
;         tile[kk * 65 + n4 + 0] = v[0]; tile[kk * 65 + n4 + 1] = v[1]; tile[kk * 65 + n4 + 2] = v[2]; tile[kk * 65 + n4 + 3] = v[3]; }
.Ltc2_d14:
	v_mov_b32_e32 v42, 0
	v_mov_b32_e32 v43, 0
	v_mov_b32_e32 v44, 0
	v_mov_b32_e32 v45, 0
	v_mov_b32_e32 v46, 0
	v_mov_b32_e32 v47, 0
	v_mov_b32_e32 v48, 0
	v_mov_b32_e32 v49, 0
	v_mul_u32_u24_e32 v26, s28, v20
	v_add_lshl_u32 v26, v26, v21, 2
	s_lshl_b32 s0, s28, 7
	v_add_u32_e32 v27, s0, v26
	v_cmp_gt_i32_e32 vcc, s29, v21
	s_and_saveexec_b64 s[0:1], vcc
	global_load_dwordx4 v[42:45], v26, s[26:27]
	global_load_dwordx4 v[46:49], v27, s[26:27]
	s_mov_b64 exec, s[0:1]
	s_add_u32 s24, s24, 0xe0
	s_min_u32 s0, s24, 4479
	s_mov_b32 s21, s0
	s_mov_b32 s0, s21
	s_cmpk_lt_u32 s0, 9600
	s_cbranch_scc0 .Ltc2_c28
	s_and_b32 s1, s0, 31
	s_lshl_b32 s1, s1, 6
	s_lshr_b32 s21, s0, 5
	s_lshl_b32 s21, s21, 6
	s_movk_i32 s29, 64
	s_cmpk_lt_u32 s21, 7680
	s_cbranch_scc1 .Ltc2_n30
	s_cmpk_lt_u32 s21, 18944
	s_cbranch_scc0 .Ltc2_t29
	s_add_u32 s21, s21, 48
	s_branch .Ltc2_n30

; __device__ __forceinline__ void tconv_tile(LAS float* tile, const float* src, int ld, int k0, int n0, int mode, bf16_t* dst, int K) {
;     ...
;     for (int it = 0; it < 2; ++it) { const int idx = tid + it * 512, kk = idx >> 4, n4 = (idx & 15) * 4, nn = n0 + n4; int oc = nn; bool valid = true;
;         if (mode == 1) { if (nn < 7680) oc = nn; else if (nn < 18944) oc = nn + 48; else if (nn < INW) oc = 7680 + (nn - 18944); else valid = false; }
;         f32x4 v = (f32x4){0.f, 0.f, 0.f, 0.f}; if (valid) v = *(const f32x4*)(src + (size_t)(k0 + kk) * ld + oc);
;         tile[kk * 65 + n4 + 0] = v[0]; tile[kk * 65 + n4 + 1] = v[1]; tile[kk * 65 + n4 + 2] = v[2]; tile[kk * 65 + n4 + 3] = v[3]; }
.Ltc2_d27:
	v_mov_b32_e32 v50, 0
	v_mov_b32_e32 v51, 0
	v_mov_b32_e32 v52, 0
	v_mov_b32_e32 v53, 0
	v_mov_b32_e32 v54, 0
	v_mov_b32_e32 v55, 0
	v_mov_b32_e32 v56, 0
	v_mov_b32_e32 v57, 0
	v_mul_u32_u24_e32 v26, s28, v20
	v_add_lshl_u32 v26, v26, v21, 2
	s_lshl_b32 s0, s28, 7
	v_add_u32_e32 v27, s0, v26
	v_cmp_gt_i32_e32 vcc, s29, v21
	s_and_saveexec_b64 s[0:1], vcc
	global_load_dwordx4 v[50:53], v26, s[26:27]
	global_load_dwordx4 v[54:57], v27, s[26:27]
	s_mov_b64 exec, s[0:1]
	s_add_u32 s24, s24, 0xe0
	s_min_u32 s0, s24, 4479
	s_mov_b32 s21, s0
	s_mov_b32 s0, s21
	s_cmpk_lt_u32 s0, 9600
	s_cbranch_scc0 .Ltc2_c41
	s_and_b32 s1, s0, 31
	s_lshl_b32 s1, s1, 6
	s_lshr_b32 s21, s0, 5
	s_lshl_b32 s21, s21, 6
	s_movk_i32 s29, 64
	s_cmpk_lt_u32 s21, 7680
	s_cbranch_scc1 .Ltc2_n43
	s_cmpk_lt_u32 s21, 18944
	s_cbranch_scc0 .Ltc2_t42
	s_add_u32 s21, s21, 48
	s_branch .Ltc2_n43

; __device__ __forceinline__ void tconv_tile(LAS float* tile, const float* src, int ld, int k0, int n0, int mode, bf16_t* dst, int K) {
;     ...
;     for (int it = 0; it < 2; ++it) { const int idx = tid + it * 512, kk = idx >> 4, n4 = (idx & 15) * 4, nn = n0 + n4; int oc = nn; bool valid = true;
;         if (mode == 1) { if (nn < 7680) oc = nn; else if (nn < 18944) oc = nn + 48; else if (nn < INW) oc = 7680 + (nn - 18944); else valid = false; }
;         f32x4 v = (f32x4){0.f, 0.f, 0.f, 0.f}; if (valid) v = *(const f32x4*)(src + (size_t)(k0 + kk) * ld + oc);
;         tile[kk * 65 + n4 + 0] = v[0]; tile[kk * 65 + n4 + 1] = v[1]; tile[kk * 65 + n4 + 2] = v[2]; tile[kk * 65 + n4 + 3] = v[3]; }
.Ltc2_d40:
	v_mov_b32_e32 v58, 0
	v_mov_b32_e32 v59, 0
	v_mov_b32_e32 v60, 0
	v_mov_b32_e32 v61, 0
	v_mov_b32_e32 v62, 0
	v_mov_b32_e32 v63, 0
	v_mov_b32_e32 v64, 0
	v_mov_b32_e32 v65, 0
	v_mul_u32_u24_e32 v26, s28, v20
	v_add_lshl_u32 v26, v26, v21, 2
	s_lshl_b32 s0, s28, 7
	v_add_u32_e32 v27, s0, v26
	v_cmp_gt_i32_e32 vcc, s29, v21
	s_and_saveexec_b64 s[0:1], vcc
	global_load_dwordx4 v[58:61], v26, s[26:27]
	global_load_dwordx4 v[62:65], v27, s[26:27]
	s_mov_b64 exec, s[0:1]
	s_add_u32 s24, s24, 0xe0
	s_min_u32 s0, s24, 4479
	s_mov_b32 s21, s0
	s_mov_b32 s0, s21
	s_cmpk_lt_u32 s0, 9600
	s_cbranch_scc0 .Ltc2_c54
	s_and_b32 s1, s0, 31
	s_lshl_b32 s1, s1, 6
	s_lshr_b32 s21, s0, 5
	s_lshl_b32 s21, s21, 6
	s_movk_i32 s29, 64
	s_cmpk_lt_u32 s21, 7680
	s_cbranch_scc1 .Ltc2_n56
	s_cmpk_lt_u32 s21, 18944
	s_cbranch_scc0 .Ltc2_t55
	s_add_u32 s21, s21, 48
	s_branch .Ltc2_n56

; __device__ __forceinline__ void tconv_tile(LAS float* tile, const float* src, int ld, int k0, int n0, int mode, bf16_t* dst, int K) {
;     ...
;     for (int it = 0; it < 2; ++it) { const int idx = tid + it * 512, kk = idx >> 4, n4 = (idx & 15) * 4, nn = n0 + n4; int oc = nn; bool valid = true;
;         if (mode == 1) { if (nn < 7680) oc = nn; else if (nn < 18944) oc = nn + 48; else if (nn < INW) oc = 7680 + (nn - 18944); else valid = false; }
;         f32x4 v = (f32x4){0.f, 0.f, 0.f, 0.f}; if (valid) v = *(const f32x4*)(src + (size_t)(k0 + kk) * ld + oc);
;         tile[kk * 65 + n4 + 0] = v[0]; tile[kk * 65 + n4 + 1] = v[1]; tile[kk * 65 + n4 + 2] = v[2]; tile[kk * 65 + n4 + 3] = v[3]; }
.Ltc2_d53:
	v_mov_b32_e32 v78, 0
	v_mov_b32_e32 v79, 0
	v_mov_b32_e32 v80, 0
	v_mov_b32_e32 v81, 0
	v_mov_b32_e32 v82, 0
	v_mov_b32_e32 v83, 0
	v_mov_b32_e32 v84, 0
	v_mov_b32_e32 v85, 0
	v_mul_u32_u24_e32 v26, s28, v20
	v_add_lshl_u32 v26, v26, v21, 2
	s_lshl_b32 s0, s28, 7
	v_add_u32_e32 v27, s0, v26
	v_cmp_gt_i32_e32 vcc, s29, v21
	s_and_saveexec_b64 s[0:1], vcc
	global_load_dwordx4 v[78:81], v26, s[26:27]
	global_load_dwordx4 v[82:85], v27, s[26:27]
	s_mov_b64 exec, s[0:1]
	s_add_u32 s24, s24, 0xe0
	s_min_u32 s0, s24, 4479
	s_mov_b32 s21, s0
	s_mov_b32 s0, s21
	s_cmpk_lt_u32 s0, 9600
	s_cbranch_scc0 .Ltc2_c67
	s_and_b32 s1, s0, 31
	s_lshl_b32 s1, s1, 6
	s_lshr_b32 s21, s0, 5
	s_lshl_b32 s21, s21, 6
	s_movk_i32 s29, 64
	s_cmpk_lt_u32 s21, 7680
	s_cbranch_scc1 .Ltc2_n69
	s_cmpk_lt_u32 s21, 18944
	s_cbranch_scc0 .Ltc2_t68
	s_add_u32 s21, s21, 48
	s_branch .Ltc2_n69

; __device__ __forceinline__ void tconv_tile(LAS float* tile, const float* src, int ld, int k0, int n0, int mode, bf16_t* dst, int K) {
;     ...
;     for (int it = 0; it < 2; ++it) { const int idx = tid + it * 512, kk = idx >> 4, n4 = (idx & 15) * 4, nn = n0 + n4; int oc = nn; bool valid = true;
;         if (mode == 1) { if (nn < 7680) oc = nn; else if (nn < 18944) oc = nn + 48; else if (nn < INW) oc = 7680 + (nn - 18944); else valid = false; }
;         f32x4 v = (f32x4){0.f, 0.f, 0.f, 0.f}; if (valid) v = *(const f32x4*)(src + (size_t)(k0 + kk) * ld + oc);
;         tile[kk * 65 + n4 + 0] = v[0]; tile[kk * 65 + n4 + 1] = v[1]; tile[kk * 65 + n4 + 2] = v[2]; tile[kk * 65 + n4 + 3] = v[3]; }
.Ltc2_d66:
	v_mov_b32_e32 v86, 0
	v_mov_b32_e32 v87, 0
	v_mov_b32_e32 v88, 0
	v_mov_b32_e32 v89, 0
	v_mov_b32_e32 v90, 0
	v_mov_b32_e32 v91, 0
	v_mov_b32_e32 v92, 0
	v_mov_b32_e32 v93, 0
	v_mul_u32_u24_e32 v26, s28, v20
	v_add_lshl_u32 v26, v26, v21, 2
	s_lshl_b32 s0, s28, 7
	v_add_u32_e32 v27, s0, v26
	v_cmp_gt_i32_e32 vcc, s29, v21
	s_and_saveexec_b64 s[0:1], vcc
	global_load_dwordx4 v[86:89], v26, s[26:27]
	global_load_dwordx4 v[90:93], v27, s[26:27]
	s_mov_b64 exec, s[0:1]
	s_add_u32 s24, s24, 0xe0
	s_cmpk_ge_u32 s25, 4480
	s_cbranch_scc1 .Ltc2_exit
	s_waitcnt vmcnt(10)
	v_add_u32_e32 v28, 0, v22
	ds_write2_b32 v28, v34, v35 offset1:1
	ds_write2_b32 v28, v36, v37 offset0:2 offset1:3
	v_add_u32_e32 v28, 0x2080, v28
	ds_write2_b32 v28, v38, v39 offset1:1
	ds_write2_b32 v28, v40, v41 offset0:2 offset1:3
	s_mov_b32 s21, s25
	s_mov_b32 s0, s21
	s_cmpk_lt_u32 s0, 9600
	s_cbranch_scc0 .Ltc2_c80
	s_and_b32 s1, s0, 31
	s_lshl_b32 s1, s1, 6
	s_lshr_b32 s21, s0, 5
	s_lshl_b32 s21, s21, 17
	s_add_u32 s1, s1, s21
	s_lshl_b32 s1, s1, 1
	s_add_u32 s1, s1, 0x4001000
	s_add_u32 s30, s68, s1
	s_addc_u32 s31, s69, 0
	s_movk_i32 s20, 0x800
	s_branch .Ltc2_d79

; __device__ __forceinline__ unsigned cvt_pk_bf16(float lo, float hi) { unsigned r; asm("v_cvt_pk_bf16_f32 %0, %1, %2" : "=v"(r) : "v"(lo), "v"(hi)); return r; }
; __device__ __forceinline__ void tconv_tile(LAS float* tile, const float* src, int ld, int k0, int n0, int mode, bf16_t* dst, int K) {
;     ...
;     { const int n = tid >> 3, k8 = (tid & 7) * 8; float v[8];
; #pragma unroll
;         for (int e = 0; e < 8; ++e) v[e] = tile[(k8 + e) * 65 + n];
;         u32x4 w; w.x = cvt_pk_bf16(v[0], v[1]); w.y = cvt_pk_bf16(v[2], v[3]); w.z = cvt_pk_bf16(v[4], v[5]); w.w = cvt_pk_bf16(v[6], v[7]);
;         *(u32x4*)(dst + (size_t)(n0 + n) * K + k0 + k8) = w; }
;     __syncthreads();
.Ltc2_d79:
	v_mul_u32_u24_e32 v29, s20, v24
	v_add_lshl_u32 v29, v29, v25, 1
	s_waitcnt lgkmcnt(0)
	s_barrier
	v_add_u32_e32 v28, 0, v23
	ds_read2_b32 v[2:3], v28 offset1:65
	ds_read2_b32 v[4:5], v28 offset0:130 offset1:195
	v_add_u32_e32 v28, 0x400, v28
	ds_read2_b32 v[6:7], v28 offset0:4 offset1:69
	ds_read2_b32 v[10:11], v28 offset0:134 offset1:199
	s_waitcnt lgkmcnt(3)
	v_cvt_pk_bf16_f32 v2, v2, v3
	s_waitcnt lgkmcnt(2)
	v_cvt_pk_bf16_f32 v3, v4, v5
	s_waitcnt lgkmcnt(1)
	v_cvt_pk_bf16_f32 v4, v6, v7
	s_waitcnt lgkmcnt(0)
	v_cvt_pk_bf16_f32 v5, v10, v11
	global_store_dwordx4 v29, v[2:5], s[30:31]
	s_add_u32 s25, s25, 0xe0
	s_min_u32 s0, s24, 4479
	s_mov_b32 s21, s0
	s_mov_b32 s0, s21
	s_cmpk_lt_u32 s0, 9600
	s_cbranch_scc0 .Ltc2_c87
	s_and_b32 s1, s0, 31
	s_lshl_b32 s1, s1, 6
	s_lshr_b32 s21, s0, 5
	s_lshl_b32 s21, s21, 6
	s_movk_i32 s29, 64
	s_cmpk_lt_u32 s21, 7680
	s_cbranch_scc1 .Ltc2_n89
	s_cmpk_lt_u32 s21, 18944
	s_cbranch_scc0 .Ltc2_t88
	s_add_u32 s21, s21, 48
	s_branch .Ltc2_n89

; __device__ __forceinline__ unsigned cvt_pk_bf16(float lo, float hi) { unsigned r; asm("v_cvt_pk_bf16_f32 %0, %1, %2" : "=v"(r) : "v"(lo), "v"(hi)); return r; }
; __device__ __forceinline__ void tconv_tile(LAS float* tile, const float* src, int ld, int k0, int n0, int mode, bf16_t* dst, int K) {
;     ...
;     for (int it = 0; it < 2; ++it) { const int idx = tid + it * 512, kk = idx >> 4, n4 = (idx & 15) * 4, nn = n0 + n4; int oc = nn; bool valid = true;
;         if (mode == 1) { if (nn < 7680) oc = nn; else if (nn < 18944) oc = nn + 48; else if (nn < INW) oc = 7680 + (nn - 18944); else valid = false; }
;         f32x4 v = (f32x4){0.f, 0.f, 0.f, 0.f}; if (valid) v = *(const f32x4*)(src + (size_t)(k0 + kk) * ld + oc);
;         tile[kk * 65 + n4 + 0] = v[0]; tile[kk * 65 + n4 + 1] = v[1]; tile[kk * 65 + n4 + 2] = v[2]; tile[kk * 65 + n4 + 3] = v[3]; }
;     __syncthreads();
;     { const int n = tid >> 3, k8 = (tid & 7) * 8; float v[8];
; #pragma unroll
;         for (int e = 0; e < 8; ++e) v[e] = tile[(k8 + e) * 65 + n];
;         u32x4 w; w.x = cvt_pk_bf16(v[0], v[1]); w.y = cvt_pk_bf16(v[2], v[3]); w.z = cvt_pk_bf16(v[4], v[5]); w.w = cvt_pk_bf16(v[6], v[7]);
;         *(u32x4*)(dst + (size_t)(n0 + n) * K + k0 + k8) = w; }
; __device__ __forceinline__ void prologue(LAS unsigned char* lds, const Ctx& P, int l) {
;     ...
;     for (int t = blockIdx.x; t < T_ALL; t += G) {
;         int q = t;
;         if (q < T_IN) { const int kt = q & 31, ntl = q >> 5; tconv_tile(tile, P.in[3] + (size_t)l * DM * INW, INW, kt * 64, ntl * 64, 1, (bf16_t*)(ws + WS_WIN), DM); continue; }
.Ltc2_d86:
	v_mov_b32_e32 v34, 0
	v_mov_b32_e32 v35, 0
	v_mov_b32_e32 v36, 0
	v_mov_b32_e32 v37, 0
	v_mov_b32_e32 v38, 0
	v_mov_b32_e32 v39, 0
	v_mov_b32_e32 v40, 0
	v_mov_b32_e32 v41, 0
	v_mul_u32_u24_e32 v26, s28, v20
	v_add_lshl_u32 v26, v26, v21, 2
	s_lshl_b32 s0, s28, 7
	v_add_u32_e32 v27, s0, v26
	v_cmp_gt_i32_e32 vcc, s29, v21
	s_and_saveexec_b64 s[0:1], vcc
	global_load_dwordx4 v[34:37], v26, s[26:27]
	global_load_dwordx4 v[38:41], v27, s[26:27]
	s_mov_b64 exec, s[0:1]
	s_add_u32 s24, s24, 0xe0
	s_cmpk_ge_u32 s25, 4480
	s_cbranch_scc1 .Ltc2_exit
	s_waitcnt vmcnt(11)
	v_add_u32_e32 v28, 16896, v22
	ds_write2_b32 v28, v42, v43 offset1:1
	ds_write2_b32 v28, v44, v45 offset0:2 offset1:3
	v_add_u32_e32 v28, 0x2080, v28
	ds_write2_b32 v28, v46, v47 offset1:1
	ds_write2_b32 v28, v48, v49 offset0:2 offset1:3
	s_mov_b32 s21, s25
	s_mov_b32 s0, s21
	s_cmpk_lt_u32 s0, 9600
	s_cbranch_scc0 .Ltc2_c100
	s_and_b32 s1, s0, 31
	s_lshl_b32 s1, s1, 6
	s_lshr_b32 s21, s0, 5
	s_lshl_b32 s21, s21, 17
	s_add_u32 s1, s1, s21
	s_lshl_b32 s1, s1, 1
	s_add_u32 s1, s1, 0x4001000
	s_add_u32 s30, s68, s1
	s_addc_u32 s31, s69, 0
	s_movk_i32 s20, 0x800
	s_branch .Ltc2_d99

; __device__ __forceinline__ unsigned cvt_pk_bf16(float lo, float hi) { unsigned r; asm("v_cvt_pk_bf16_f32 %0, %1, %2" : "=v"(r) : "v"(lo), "v"(hi)); return r; }
; __device__ __forceinline__ void tconv_tile(LAS float* tile, const float* src, int ld, int k0, int n0, int mode, bf16_t* dst, int K) {
;     ...
;     for (int it = 0; it < 2; ++it) { const int idx = tid + it * 512, kk = idx >> 4, n4 = (idx & 15) * 4, nn = n0 + n4; int oc = nn; bool valid = true;
;         if (mode == 1) { if (nn < 7680) oc = nn; else if (nn < 18944) oc = nn + 48; else if (nn < INW) oc = 7680 + (nn - 18944); else valid = false; }
;         f32x4 v = (f32x4){0.f, 0.f, 0.f, 0.f}; if (valid) v = *(const f32x4*)(src + (size_t)(k0 + kk) * ld + oc);
;         tile[kk * 65 + n4 + 0] = v[0]; tile[kk * 65 + n4 + 1] = v[1]; tile[kk * 65 + n4 + 2] = v[2]; tile[kk * 65 + n4 + 3] = v[3]; }
;     __syncthreads();
;     { const int n = tid >> 3, k8 = (tid & 7) * 8; float v[8];
; #pragma unroll
;         for (int e = 0; e < 8; ++e) v[e] = tile[(k8 + e) * 65 + n];
;         u32x4 w; w.x = cvt_pk_bf16(v[0], v[1]); w.y = cvt_pk_bf16(v[2], v[3]); w.z = cvt_pk_bf16(v[4], v[5]); w.w = cvt_pk_bf16(v[6], v[7]);
;         *(u32x4*)(dst + (size_t)(n0 + n) * K + k0 + k8) = w; }
.Ltc2_d99:
	v_mul_u32_u24_e32 v29, s20, v24
	v_add_lshl_u32 v29, v29, v25, 1
	s_waitcnt lgkmcnt(0)
	s_barrier
	v_add_u32_e32 v28, 16896, v23
	ds_read2_b32 v[2:3], v28 offset1:65
	ds_read2_b32 v[4:5], v28 offset0:130 offset1:195
	v_add_u32_e32 v28, 0x400, v28
	ds_read2_b32 v[6:7], v28 offset0:4 offset1:69
	ds_read2_b32 v[10:11], v28 offset0:134 offset1:199
	s_waitcnt lgkmcnt(3)
	v_cvt_pk_bf16_f32 v2, v2, v3
	s_waitcnt lgkmcnt(2)
	v_cvt_pk_bf16_f32 v3, v4, v5
	s_waitcnt lgkmcnt(1)
	v_cvt_pk_bf16_f32 v4, v6, v7
	s_waitcnt lgkmcnt(0)
	v_cvt_pk_bf16_f32 v5, v10, v11
	global_store_dwordx4 v29, v[2:5], s[30:31]
	s_add_u32 s25, s25, 0xe0
	s_min_u32 s0, s24, 4479
	s_mov_b32 s21, s0
	s_mov_b32 s0, s21
	s_cmpk_lt_u32 s0, 9600
	s_cbranch_scc0 .Ltc2_c107
	s_and_b32 s1, s0, 31
	s_lshl_b32 s1, s1, 6
	s_lshr_b32 s21, s0, 5
	s_lshl_b32 s21, s21, 6
	s_movk_i32 s29, 64
	s_cmpk_lt_u32 s21, 7680
	s_cbranch_scc1 .Ltc2_n109
	s_cmpk_lt_u32 s21, 18944
	s_cbranch_scc0 .Ltc2_t108
	s_add_u32 s21, s21, 48
	s_branch .Ltc2_n109

; __device__ __forceinline__ unsigned cvt_pk_bf16(float lo, float hi) { unsigned r; asm("v_cvt_pk_bf16_f32 %0, %1, %2" : "=v"(r) : "v"(lo), "v"(hi)); return r; }
; __device__ __forceinline__ void tconv_tile(LAS float* tile, const float* src, int ld, int k0, int n0, int mode, bf16_t* dst, int K) {
;     ...
;     for (int it = 0; it < 2; ++it) { const int idx = tid + it * 512, kk = idx >> 4, n4 = (idx & 15) * 4, nn = n0 + n4; int oc = nn; bool valid = true;
;         if (mode == 1) { if (nn < 7680) oc = nn; else if (nn < 18944) oc = nn + 48; else if (nn < INW) oc = 7680 + (nn - 18944); else valid = false; }
;         f32x4 v = (f32x4){0.f, 0.f, 0.f, 0.f}; if (valid) v = *(const f32x4*)(src + (size_t)(k0 + kk) * ld + oc);
;         tile[kk * 65 + n4 + 0] = v[0]; tile[kk * 65 + n4 + 1] = v[1]; tile[kk * 65 + n4 + 2] = v[2]; tile[kk * 65 + n4 + 3] = v[3]; }
;     __syncthreads();
;     { const int n = tid >> 3, k8 = (tid & 7) * 8; float v[8];
; #pragma unroll
;         for (int e = 0; e < 8; ++e) v[e] = tile[(k8 + e) * 65 + n];
;         u32x4 w; w.x = cvt_pk_bf16(v[0], v[1]); w.y = cvt_pk_bf16(v[2], v[3]); w.z = cvt_pk_bf16(v[4], v[5]); w.w = cvt_pk_bf16(v[6], v[7]);
;         *(u32x4*)(dst + (size_t)(n0 + n) * K + k0 + k8) = w; }
; __device__ __forceinline__ void prologue(LAS unsigned char* lds, const Ctx& P, int l) {
;     ...
;     for (int t = blockIdx.x; t < T_ALL; t += G) {
;         int q = t;
;         if (q < T_IN) { const int kt = q & 31, ntl = q >> 5; tconv_tile(tile, P.in[3] + (size_t)l * DM * INW, INW, kt * 64, ntl * 64, 1, (bf16_t*)(ws + WS_WIN), DM); continue; }
.Ltc2_d106:
	v_mov_b32_e32 v42, 0
	v_mov_b32_e32 v43, 0
	v_mov_b32_e32 v44, 0
	v_mov_b32_e32 v45, 0
	v_mov_b32_e32 v46, 0
	v_mov_b32_e32 v47, 0
	v_mov_b32_e32 v48, 0
	v_mov_b32_e32 v49, 0
	v_mul_u32_u24_e32 v26, s28, v20
	v_add_lshl_u32 v26, v26, v21, 2
	s_lshl_b32 s0, s28, 7
	v_add_u32_e32 v27, s0, v26
	v_cmp_gt_i32_e32 vcc, s29, v21
	s_and_saveexec_b64 s[0:1], vcc
	global_load_dwordx4 v[42:45], v26, s[26:27]
	global_load_dwordx4 v[46:49], v27, s[26:27]
	s_mov_b64 exec, s[0:1]
	s_add_u32 s24, s24, 0xe0
	s_cmpk_ge_u32 s25, 4480
	s_cbranch_scc1 .Ltc2_exit
	s_waitcnt vmcnt(12)
	v_add_u32_e32 v28, 0, v22
	ds_write2_b32 v28, v50, v51 offset1:1
	ds_write2_b32 v28, v52, v53 offset0:2 offset1:3
	v_add_u32_e32 v28, 0x2080, v28
	ds_write2_b32 v28, v54, v55 offset1:1
	ds_write2_b32 v28, v56, v57 offset0:2 offset1:3
	s_mov_b32 s21, s25
	s_mov_b32 s0, s21
	s_cmpk_lt_u32 s0, 9600
	s_cbranch_scc0 .Ltc2_c120
	s_and_b32 s1, s0, 31
	s_lshl_b32 s1, s1, 6
	s_lshr_b32 s21, s0, 5
	s_lshl_b32 s21, s21, 17
	s_add_u32 s1, s1, s21
	s_lshl_b32 s1, s1, 1
	s_add_u32 s1, s1, 0x4001000
	s_add_u32 s30, s68, s1
	s_addc_u32 s31, s69, 0
	s_movk_i32 s20, 0x800
	s_branch .Ltc2_d119

; __device__ __forceinline__ unsigned cvt_pk_bf16(float lo, float hi) { unsigned r; asm("v_cvt_pk_bf16_f32 %0, %1, %2" : "=v"(r) : "v"(lo), "v"(hi)); return r; }
; __device__ __forceinline__ void tconv_tile(LAS float* tile, const float* src, int ld, int k0, int n0, int mode, bf16_t* dst, int K) {
;     ...
;     for (int it = 0; it < 2; ++it) { const int idx = tid + it * 512, kk = idx >> 4, n4 = (idx & 15) * 4, nn = n0 + n4; int oc = nn; bool valid = true;
;         if (mode == 1) { if (nn < 7680) oc = nn; else if (nn < 18944) oc = nn + 48; else if (nn < INW) oc = 7680 + (nn - 18944); else valid = false; }
;         f32x4 v = (f32x4){0.f, 0.f, 0.f, 0.f}; if (valid) v = *(const f32x4*)(src + (size_t)(k0 + kk) * ld + oc);
;         tile[kk * 65 + n4 + 0] = v[0]; tile[kk * 65 + n4 + 1] = v[1]; tile[kk * 65 + n4 + 2] = v[2]; tile[kk * 65 + n4 + 3] = v[3]; }
;     __syncthreads();
;     { const int n = tid >> 3, k8 = (tid & 7) * 8; float v[8];
; #pragma unroll
;         for (int e = 0; e < 8; ++e) v[e] = tile[(k8 + e) * 65 + n];
;         u32x4 w; w.x = cvt_pk_bf16(v[0], v[1]); w.y = cvt_pk_bf16(v[2], v[3]); w.z = cvt_pk_bf16(v[4], v[5]); w.w = cvt_pk_bf16(v[6], v[7]);
;         *(u32x4*)(dst + (size_t)(n0 + n) * K + k0 + k8) = w; }
; __device__ __forceinline__ void prologue(LAS unsigned char* lds, const Ctx& P, int l) {
;     ...
;     for (int t = blockIdx.x; t < T_ALL; t += G) {
;         int q = t;
;         if (q < T_IN) { const int kt = q & 31, ntl = q >> 5; tconv_tile(tile, P.in[3] + (size_t)l * DM * INW, INW, kt * 64, ntl * 64, 1, (bf16_t*)(ws + WS_WIN), DM); continue; }
.Ltc2_d126:
	v_mov_b32_e32 v50, 0
	v_mov_b32_e32 v51, 0
	v_mov_b32_e32 v52, 0
	v_mov_b32_e32 v53, 0
	v_mov_b32_e32 v54, 0
	v_mov_b32_e32 v55, 0
	v_mov_b32_e32 v56, 0
	v_mov_b32_e32 v57, 0
	v_mul_u32_u24_e32 v26, s28, v20
	v_add_lshl_u32 v26, v26, v21, 2
	s_lshl_b32 s0, s28, 7
	v_add_u32_e32 v27, s0, v26
	v_cmp_gt_i32_e32 vcc, s29, v21
	s_and_saveexec_b64 s[0:1], vcc
	global_load_dwordx4 v[50:53], v26, s[26:27]
	global_load_dwordx4 v[54:57], v27, s[26:27]
	s_mov_b64 exec, s[0:1]
	s_add_u32 s24, s24, 0xe0
	s_cmpk_ge_u32 s25, 4480
	s_cbranch_scc1 .Ltc2_exit
	s_waitcnt vmcnt(13)
	v_add_u32_e32 v28, 16896, v22
	ds_write2_b32 v28, v58, v59 offset1:1
	ds_write2_b32 v28, v60, v61 offset0:2 offset1:3
	v_add_u32_e32 v28, 0x2080, v28
	ds_write2_b32 v28, v62, v63 offset1:1
	ds_write2_b32 v28, v64, v65 offset0:2 offset1:3
	s_mov_b32 s21, s25
	s_mov_b32 s0, s21
	s_cmpk_lt_u32 s0, 9600
	s_cbranch_scc0 .Ltc2_c140
	s_and_b32 s1, s0, 31
	s_lshl_b32 s1, s1, 6
	s_lshr_b32 s21, s0, 5
	s_lshl_b32 s21, s21, 17
	s_add_u32 s1, s1, s21
	s_lshl_b32 s1, s1, 1
	s_add_u32 s1, s1, 0x4001000
	s_add_u32 s30, s68, s1
	s_addc_u32 s31, s69, 0
	s_movk_i32 s20, 0x800
	s_branch .Ltc2_d139

; __device__ __forceinline__ unsigned cvt_pk_bf16(float lo, float hi) { unsigned r; asm("v_cvt_pk_bf16_f32 %0, %1, %2" : "=v"(r) : "v"(lo), "v"(hi)); return r; }
; __device__ __forceinline__ void tconv_tile(LAS float* tile, const float* src, int ld, int k0, int n0, int mode, bf16_t* dst, int K) {
;     ...
;     for (int it = 0; it < 2; ++it) { const int idx = tid + it * 512, kk = idx >> 4, n4 = (idx & 15) * 4, nn = n0 + n4; int oc = nn; bool valid = true;
;         if (mode == 1) { if (nn < 7680) oc = nn; else if (nn < 18944) oc = nn + 48; else if (nn < INW) oc = 7680 + (nn - 18944); else valid = false; }
;         f32x4 v = (f32x4){0.f, 0.f, 0.f, 0.f}; if (valid) v = *(const f32x4*)(src + (size_t)(k0 + kk) * ld + oc);
;         tile[kk * 65 + n4 + 0] = v[0]; tile[kk * 65 + n4 + 1] = v[1]; tile[kk * 65 + n4 + 2] = v[2]; tile[kk * 65 + n4 + 3] = v[3]; }
;     __syncthreads();
;     { const int n = tid >> 3, k8 = (tid & 7) * 8; float v[8];
; #pragma unroll
;         for (int e = 0; e < 8; ++e) v[e] = tile[(k8 + e) * 65 + n];
;         u32x4 w; w.x = cvt_pk_bf16(v[0], v[1]); w.y = cvt_pk_bf16(v[2], v[3]); w.z = cvt_pk_bf16(v[4], v[5]); w.w = cvt_pk_bf16(v[6], v[7]);
;         *(u32x4*)(dst + (size_t)(n0 + n) * K + k0 + k8) = w; }
; __device__ __forceinline__ void prologue(LAS unsigned char* lds, const Ctx& P, int l) {
;     ...
;     for (int t = blockIdx.x; t < T_ALL; t += G) {
;         int q = t;
;         if (q < T_IN) { const int kt = q & 31, ntl = q >> 5; tconv_tile(tile, P.in[3] + (size_t)l * DM * INW, INW, kt * 64, ntl * 64, 1, (bf16_t*)(ws + WS_WIN), DM); continue; }
.Ltc2_d146:
	v_mov_b32_e32 v58, 0
	v_mov_b32_e32 v59, 0
	v_mov_b32_e32 v60, 0
	v_mov_b32_e32 v61, 0
	v_mov_b32_e32 v62, 0
	v_mov_b32_e32 v63, 0
	v_mov_b32_e32 v64, 0
	v_mov_b32_e32 v65, 0
	v_mul_u32_u24_e32 v26, s28, v20
	v_add_lshl_u32 v26, v26, v21, 2
	s_lshl_b32 s0, s28, 7
	v_add_u32_e32 v27, s0, v26
	v_cmp_gt_i32_e32 vcc, s29, v21
	s_and_saveexec_b64 s[0:1], vcc
	global_load_dwordx4 v[58:61], v26, s[26:27]
	global_load_dwordx4 v[62:65], v27, s[26:27]
	s_mov_b64 exec, s[0:1]
	s_add_u32 s24, s24, 0xe0
	s_cmpk_ge_u32 s25, 4480
	s_cbranch_scc1 .Ltc2_exit
	s_waitcnt vmcnt(14)
	v_add_u32_e32 v28, 0, v22
	ds_write2_b32 v28, v78, v79 offset1:1
	ds_write2_b32 v28, v80, v81 offset0:2 offset1:3
	v_add_u32_e32 v28, 0x2080, v28
	ds_write2_b32 v28, v82, v83 offset1:1
	ds_write2_b32 v28, v84, v85 offset0:2 offset1:3
	s_mov_b32 s21, s25
	s_mov_b32 s0, s21
	s_cmpk_lt_u32 s0, 9600
	s_cbranch_scc0 .Ltc2_c160
	s_and_b32 s1, s0, 31
	s_lshl_b32 s1, s1, 6
	s_lshr_b32 s21, s0, 5
	s_lshl_b32 s21, s21, 17
	s_add_u32 s1, s1, s21
	s_lshl_b32 s1, s1, 1
	s_add_u32 s1, s1, 0x4001000
	s_add_u32 s30, s68, s1
	s_addc_u32 s31, s69, 0
	s_movk_i32 s20, 0x800
	s_branch .Ltc2_d159

; __device__ __forceinline__ unsigned cvt_pk_bf16(float lo, float hi) { unsigned r; asm("v_cvt_pk_bf16_f32 %0, %1, %2" : "=v"(r) : "v"(lo), "v"(hi)); return r; }
; __device__ __forceinline__ void tconv_tile(LAS float* tile, const float* src, int ld, int k0, int n0, int mode, bf16_t* dst, int K) {
;     ...
;     for (int it = 0; it < 2; ++it) { const int idx = tid + it * 512, kk = idx >> 4, n4 = (idx & 15) * 4, nn = n0 + n4; int oc = nn; bool valid = true;
;         if (mode == 1) { if (nn < 7680) oc = nn; else if (nn < 18944) oc = nn + 48; else if (nn < INW) oc = 7680 + (nn - 18944); else valid = false; }
;         f32x4 v = (f32x4){0.f, 0.f, 0.f, 0.f}; if (valid) v = *(const f32x4*)(src + (size_t)(k0 + kk) * ld + oc);
;         tile[kk * 65 + n4 + 0] = v[0]; tile[kk * 65 + n4 + 1] = v[1]; tile[kk * 65 + n4 + 2] = v[2]; tile[kk * 65 + n4 + 3] = v[3]; }
;     __syncthreads();
;     { const int n = tid >> 3, k8 = (tid & 7) * 8; float v[8];
; #pragma unroll
;         for (int e = 0; e < 8; ++e) v[e] = tile[(k8 + e) * 65 + n];
;         u32x4 w; w.x = cvt_pk_bf16(v[0], v[1]); w.y = cvt_pk_bf16(v[2], v[3]); w.z = cvt_pk_bf16(v[4], v[5]); w.w = cvt_pk_bf16(v[6], v[7]);
;         *(u32x4*)(dst + (size_t)(n0 + n) * K + k0 + k8) = w; }
; __device__ __forceinline__ void prologue(LAS unsigned char* lds, const Ctx& P, int l) {
;     ...
;     for (int t = blockIdx.x; t < T_ALL; t += G) {
;         int q = t;
;         if (q < T_IN) { const int kt = q & 31, ntl = q >> 5; tconv_tile(tile, P.in[3] + (size_t)l * DM * INW, INW, kt * 64, ntl * 64, 1, (bf16_t*)(ws + WS_WIN), DM); continue; }
.Ltc2_d166:
	v_mov_b32_e32 v78, 0
	v_mov_b32_e32 v79, 0
	v_mov_b32_e32 v80, 0
	v_mov_b32_e32 v81, 0
	v_mov_b32_e32 v82, 0
	v_mov_b32_e32 v83, 0
	v_mov_b32_e32 v84, 0
	v_mov_b32_e32 v85, 0
	v_mul_u32_u24_e32 v26, s28, v20
	v_add_lshl_u32 v26, v26, v21, 2
	s_lshl_b32 s0, s28, 7
	v_add_u32_e32 v27, s0, v26
	v_cmp_gt_i32_e32 vcc, s29, v21
	s_and_saveexec_b64 s[0:1], vcc
	global_load_dwordx4 v[78:81], v26, s[26:27]
	global_load_dwordx4 v[82:85], v27, s[26:27]
	s_mov_b64 exec, s[0:1]
	s_add_u32 s24, s24, 0xe0
	s_cmpk_ge_u32 s25, 4480
	s_cbranch_scc1 .Ltc2_exit
	s_waitcnt vmcnt(15)
	v_add_u32_e32 v28, 16896, v22
	ds_write2_b32 v28, v86, v87 offset1:1
	ds_write2_b32 v28, v88, v89 offset0:2 offset1:3
	v_add_u32_e32 v28, 0x2080, v28
	ds_write2_b32 v28, v90, v91 offset1:1
	ds_write2_b32 v28, v92, v93 offset0:2 offset1:3
	s_mov_b32 s21, s25
	s_mov_b32 s0, s21
	s_cmpk_lt_u32 s0, 9600
	s_cbranch_scc0 .Ltc2_c180
	s_and_b32 s1, s0, 31
	s_lshl_b32 s1, s1, 6
	s_lshr_b32 s21, s0, 5
	s_lshl_b32 s21, s21, 17
	s_add_u32 s1, s1, s21
	s_lshl_b32 s1, s1, 1
	s_add_u32 s1, s1, 0x4001000
	s_add_u32 s30, s68, s1
	s_addc_u32 s31, s69, 0
	s_movk_i32 s20, 0x800
	s_branch .Ltc2_d179

; __device__ __forceinline__ unsigned cvt_pk_bf16(float lo, float hi) { unsigned r; asm("v_cvt_pk_bf16_f32 %0, %1, %2" : "=v"(r) : "v"(lo), "v"(hi)); return r; }
; __device__ __forceinline__ void tconv_tile(LAS float* tile, const float* src, int ld, int k0, int n0, int mode, bf16_t* dst, int K) {
;     ...
;     for (int it = 0; it < 2; ++it) { const int idx = tid + it * 512, kk = idx >> 4, n4 = (idx & 15) * 4, nn = n0 + n4; int oc = nn; bool valid = true;
;         if (mode == 1) { if (nn < 7680) oc = nn; else if (nn < 18944) oc = nn + 48; else if (nn < INW) oc = 7680 + (nn - 18944); else valid = false; }
;         f32x4 v = (f32x4){0.f, 0.f, 0.f, 0.f}; if (valid) v = *(const f32x4*)(src + (size_t)(k0 + kk) * ld + oc);
;         tile[kk * 65 + n4 + 0] = v[0]; tile[kk * 65 + n4 + 1] = v[1]; tile[kk * 65 + n4 + 2] = v[2]; tile[kk * 65 + n4 + 3] = v[3]; }
;     __syncthreads();
;     { const int n = tid >> 3, k8 = (tid & 7) * 8; float v[8];
; #pragma unroll
;         for (int e = 0; e < 8; ++e) v[e] = tile[(k8 + e) * 65 + n];
;         u32x4 w; w.x = cvt_pk_bf16(v[0], v[1]); w.y = cvt_pk_bf16(v[2], v[3]); w.z = cvt_pk_bf16(v[4], v[5]); w.w = cvt_pk_bf16(v[6], v[7]);
;         *(u32x4*)(dst + (size_t)(n0 + n) * K + k0 + k8) = w; }
; __device__ __forceinline__ void prologue(LAS unsigned char* lds, const Ctx& P, int l) {
;     ...
;     for (int t = blockIdx.x; t < T_ALL; t += G) {
;         int q = t;
;         if (q < T_IN) { const int kt = q & 31, ntl = q >> 5; tconv_tile(tile, P.in[3] + (size_t)l * DM * INW, INW, kt * 64, ntl * 64, 1, (bf16_t*)(ws + WS_WIN), DM); continue; }
.Ltc2_loop:
	s_cmpk_ge_u32 s25, 4480
	s_cbranch_scc1 .Ltc2_exit
	s_waitcnt vmcnt(15)
	v_add_u32_e32 v28, 0, v22
	ds_write2_b32 v28, v34, v35 offset1:1
	ds_write2_b32 v28, v36, v37 offset0:2 offset1:3
	v_add_u32_e32 v28, 0x2080, v28
	ds_write2_b32 v28, v38, v39 offset1:1
	ds_write2_b32 v28, v40, v41 offset0:2 offset1:3
	s_mov_b32 s21, s25
	s_mov_b32 s0, s21
	s_cmpk_lt_u32 s0, 9600
	s_cbranch_scc0 .Ltc2_c200
	s_and_b32 s1, s0, 31
	s_lshl_b32 s1, s1, 6
	s_lshr_b32 s21, s0, 5
	s_lshl_b32 s21, s21, 17
	s_add_u32 s1, s1, s21
	s_lshl_b32 s1, s1, 1
	s_add_u32 s1, s1, 0x4001000
	s_add_u32 s30, s68, s1
	s_addc_u32 s31, s69, 0
	s_movk_i32 s20, 0x800
	s_branch .Ltc2_d199

; __device__ __forceinline__ unsigned cvt_pk_bf16(float lo, float hi) { unsigned r; asm("v_cvt_pk_bf16_f32 %0, %1, %2" : "=v"(r) : "v"(lo), "v"(hi)); return r; }
; __device__ __forceinline__ void tconv_tile(LAS float* tile, const float* src, int ld, int k0, int n0, int mode, bf16_t* dst, int K) {
;     ...
;     for (int it = 0; it < 2; ++it) { const int idx = tid + it * 512, kk = idx >> 4, n4 = (idx & 15) * 4, nn = n0 + n4; int oc = nn; bool valid = true;
;         if (mode == 1) { if (nn < 7680) oc = nn; else if (nn < 18944) oc = nn + 48; else if (nn < INW) oc = 7680 + (nn - 18944); else valid = false; }
;         f32x4 v = (f32x4){0.f, 0.f, 0.f, 0.f}; if (valid) v = *(const f32x4*)(src + (size_t)(k0 + kk) * ld + oc);
;         tile[kk * 65 + n4 + 0] = v[0]; tile[kk * 65 + n4 + 1] = v[1]; tile[kk * 65 + n4 + 2] = v[2]; tile[kk * 65 + n4 + 3] = v[3]; }
;     __syncthreads();
;     { const int n = tid >> 3, k8 = (tid & 7) * 8; float v[8];
; #pragma unroll
;         for (int e = 0; e < 8; ++e) v[e] = tile[(k8 + e) * 65 + n];
;         u32x4 w; w.x = cvt_pk_bf16(v[0], v[1]); w.y = cvt_pk_bf16(v[2], v[3]); w.z = cvt_pk_bf16(v[4], v[5]); w.w = cvt_pk_bf16(v[6], v[7]);
;         *(u32x4*)(dst + (size_t)(n0 + n) * K + k0 + k8) = w; }
; __device__ __forceinline__ void prologue(LAS unsigned char* lds, const Ctx& P, int l) {
;     ...
;     for (int t = blockIdx.x; t < T_ALL; t += G) {
;         int q = t;
;         if (q < T_IN) { const int kt = q & 31, ntl = q >> 5; tconv_tile(tile, P.in[3] + (size_t)l * DM * INW, INW, kt * 64, ntl * 64, 1, (bf16_t*)(ws + WS_WIN), DM); continue; }
.Ltc2_d206:
	v_mov_b32_e32 v34, 0
	v_mov_b32_e32 v35, 0
	v_mov_b32_e32 v36, 0
	v_mov_b32_e32 v37, 0
	v_mov_b32_e32 v38, 0
	v_mov_b32_e32 v39, 0
	v_mov_b32_e32 v40, 0
	v_mov_b32_e32 v41, 0
	v_mul_u32_u24_e32 v26, s28, v20
	v_add_lshl_u32 v26, v26, v21, 2
	s_lshl_b32 s0, s28, 7
	v_add_u32_e32 v27, s0, v26
	v_cmp_gt_i32_e32 vcc, s29, v21
	s_and_saveexec_b64 s[0:1], vcc
	global_load_dwordx4 v[34:37], v26, s[26:27]
	global_load_dwordx4 v[38:41], v27, s[26:27]
	s_mov_b64 exec, s[0:1]
	s_add_u32 s24, s24, 0xe0
	s_cmpk_ge_u32 s25, 4480
	s_cbranch_scc1 .Ltc2_exit
	s_waitcnt vmcnt(15)
	v_add_u32_e32 v28, 16896, v22
	ds_write2_b32 v28, v42, v43 offset1:1
	ds_write2_b32 v28, v44, v45 offset0:2 offset1:3
	v_add_u32_e32 v28, 0x2080, v28
	ds_write2_b32 v28, v46, v47 offset1:1
	ds_write2_b32 v28, v48, v49 offset0:2 offset1:3
	s_mov_b32 s21, s25
	s_mov_b32 s0, s21
	s_cmpk_lt_u32 s0, 9600
	s_cbranch_scc0 .Ltc2_c220
	s_and_b32 s1, s0, 31
	s_lshl_b32 s1, s1, 6
	s_lshr_b32 s21, s0, 5
	s_lshl_b32 s21, s21, 17
	s_add_u32 s1, s1, s21
	s_lshl_b32 s1, s1, 1
	s_add_u32 s1, s1, 0x4001000
	s_add_u32 s30, s68, s1
	s_addc_u32 s31, s69, 0
	s_movk_i32 s20, 0x800
	s_branch .Ltc2_d219

; __device__ __forceinline__ unsigned cvt_pk_bf16(float lo, float hi) { unsigned r; asm("v_cvt_pk_bf16_f32 %0, %1, %2" : "=v"(r) : "v"(lo), "v"(hi)); return r; }
; __device__ __forceinline__ void tconv_tile(LAS float* tile, const float* src, int ld, int k0, int n0, int mode, bf16_t* dst, int K) {
;     ...
;     for (int it = 0; it < 2; ++it) { const int idx = tid + it * 512, kk = idx >> 4, n4 = (idx & 15) * 4, nn = n0 + n4; int oc = nn; bool valid = true;
;         if (mode == 1) { if (nn < 7680) oc = nn; else if (nn < 18944) oc = nn + 48; else if (nn < INW) oc = 7680 + (nn - 18944); else valid = false; }
;         f32x4 v = (f32x4){0.f, 0.f, 0.f, 0.f}; if (valid) v = *(const f32x4*)(src + (size_t)(k0 + kk) * ld + oc);
;         tile[kk * 65 + n4 + 0] = v[0]; tile[kk * 65 + n4 + 1] = v[1]; tile[kk * 65 + n4 + 2] = v[2]; tile[kk * 65 + n4 + 3] = v[3]; }
;     __syncthreads();
;     { const int n = tid >> 3, k8 = (tid & 7) * 8; float v[8];
; #pragma unroll
;         for (int e = 0; e < 8; ++e) v[e] = tile[(k8 + e) * 65 + n];
;         u32x4 w; w.x = cvt_pk_bf16(v[0], v[1]); w.y = cvt_pk_bf16(v[2], v[3]); w.z = cvt_pk_bf16(v[4], v[5]); w.w = cvt_pk_bf16(v[6], v[7]);
;         *(u32x4*)(dst + (size_t)(n0 + n) * K + k0 + k8) = w; }
; __device__ __forceinline__ void prologue(LAS unsigned char* lds, const Ctx& P, int l) {
;     ...
;     for (int t = blockIdx.x; t < T_ALL; t += G) {
;         int q = t;
;         if (q < T_IN) { const int kt = q & 31, ntl = q >> 5; tconv_tile(tile, P.in[3] + (size_t)l * DM * INW, INW, kt * 64, ntl * 64, 1, (bf16_t*)(ws + WS_WIN), DM); continue; }
.Ltc2_d226:
	v_mov_b32_e32 v42, 0
	v_mov_b32_e32 v43, 0
	v_mov_b32_e32 v44, 0
	v_mov_b32_e32 v45, 0
	v_mov_b32_e32 v46, 0
	v_mov_b32_e32 v47, 0
	v_mov_b32_e32 v48, 0
	v_mov_b32_e32 v49, 0
	v_mul_u32_u24_e32 v26, s28, v20
	v_add_lshl_u32 v26, v26, v21, 2
	s_lshl_b32 s0, s28, 7
	v_add_u32_e32 v27, s0, v26
	v_cmp_gt_i32_e32 vcc, s29, v21
	s_and_saveexec_b64 s[0:1], vcc
	global_load_dwordx4 v[42:45], v26, s[26:27]
	global_load_dwordx4 v[46:49], v27, s[26:27]
	s_mov_b64 exec, s[0:1]
	s_add_u32 s24, s24, 0xe0
	s_cmpk_ge_u32 s25, 4480
	s_cbranch_scc1 .Ltc2_exit
	s_waitcnt vmcnt(15)
	v_add_u32_e32 v28, 0, v22
	ds_write2_b32 v28, v50, v51 offset1:1
	ds_write2_b32 v28, v52, v53 offset0:2 offset1:3
	v_add_u32_e32 v28, 0x2080, v28
	ds_write2_b32 v28, v54, v55 offset1:1
	ds_write2_b32 v28, v56, v57 offset0:2 offset1:3
	s_mov_b32 s21, s25
	s_mov_b32 s0, s21
	s_cmpk_lt_u32 s0, 9600
	s_cbranch_scc0 .Ltc2_c240
	s_and_b32 s1, s0, 31
	s_lshl_b32 s1, s1, 6
	s_lshr_b32 s21, s0, 5
	s_lshl_b32 s21, s21, 17
	s_add_u32 s1, s1, s21
	s_lshl_b32 s1, s1, 1
	s_add_u32 s1, s1, 0x4001000
	s_add_u32 s30, s68, s1
	s_addc_u32 s31, s69, 0
	s_movk_i32 s20, 0x800
	s_branch .Ltc2_d239

; __device__ __forceinline__ unsigned cvt_pk_bf16(float lo, float hi) { unsigned r; asm("v_cvt_pk_bf16_f32 %0, %1, %2" : "=v"(r) : "v"(lo), "v"(hi)); return r; }
; __device__ __forceinline__ void tconv_tile(LAS float* tile, const float* src, int ld, int k0, int n0, int mode, bf16_t* dst, int K) {
;     ...
;     for (int it = 0; it < 2; ++it) { const int idx = tid + it * 512, kk = idx >> 4, n4 = (idx & 15) * 4, nn = n0 + n4; int oc = nn; bool valid = true;
;         if (mode == 1) { if (nn < 7680) oc = nn; else if (nn < 18944) oc = nn + 48; else if (nn < INW) oc = 7680 + (nn - 18944); else valid = false; }
;         f32x4 v = (f32x4){0.f, 0.f, 0.f, 0.f}; if (valid) v = *(const f32x4*)(src + (size_t)(k0 + kk) * ld + oc);
;         tile[kk * 65 + n4 + 0] = v[0]; tile[kk * 65 + n4 + 1] = v[1]; tile[kk * 65 + n4 + 2] = v[2]; tile[kk * 65 + n4 + 3] = v[3]; }
;     __syncthreads();
;     { const int n = tid >> 3, k8 = (tid & 7) * 8; float v[8];
; #pragma unroll
;         for (int e = 0; e < 8; ++e) v[e] = tile[(k8 + e) * 65 + n];
;         u32x4 w; w.x = cvt_pk_bf16(v[0], v[1]); w.y = cvt_pk_bf16(v[2], v[3]); w.z = cvt_pk_bf16(v[4], v[5]); w.w = cvt_pk_bf16(v[6], v[7]);
;         *(u32x4*)(dst + (size_t)(n0 + n) * K + k0 + k8) = w; }
; __device__ __forceinline__ void prologue(LAS unsigned char* lds, const Ctx& P, int l) {
;     ...
;     for (int t = blockIdx.x; t < T_ALL; t += G) {
;         int q = t;
;         if (q < T_IN) { const int kt = q & 31, ntl = q >> 5; tconv_tile(tile, P.in[3] + (size_t)l * DM * INW, INW, kt * 64, ntl * 64, 1, (bf16_t*)(ws + WS_WIN), DM); continue; }
.Ltc2_d246:
	v_mov_b32_e32 v50, 0
	v_mov_b32_e32 v51, 0
	v_mov_b32_e32 v52, 0
	v_mov_b32_e32 v53, 0
	v_mov_b32_e32 v54, 0
	v_mov_b32_e32 v55, 0
	v_mov_b32_e32 v56, 0
	v_mov_b32_e32 v57, 0
	v_mul_u32_u24_e32 v26, s28, v20
	v_add_lshl_u32 v26, v26, v21, 2
	s_lshl_b32 s0, s28, 7
	v_add_u32_e32 v27, s0, v26
	v_cmp_gt_i32_e32 vcc, s29, v21
	s_and_saveexec_b64 s[0:1], vcc
	global_load_dwordx4 v[50:53], v26, s[26:27]
	global_load_dwordx4 v[54:57], v27, s[26:27]
	s_mov_b64 exec, s[0:1]
	s_add_u32 s24, s24, 0xe0
	s_cmpk_ge_u32 s25, 4480
	s_cbranch_scc1 .Ltc2_exit
	s_waitcnt vmcnt(15)
	v_add_u32_e32 v28, 16896, v22
	ds_write2_b32 v28, v58, v59 offset1:1
	ds_write2_b32 v28, v60, v61 offset0:2 offset1:3
	v_add_u32_e32 v28, 0x2080, v28
	ds_write2_b32 v28, v62, v63 offset1:1
	ds_write2_b32 v28, v64, v65 offset0:2 offset1:3
	s_mov_b32 s21, s25
	s_mov_b32 s0, s21
	s_cmpk_lt_u32 s0, 9600
	s_cbranch_scc0 .Ltc2_c260
	s_and_b32 s1, s0, 31
	s_lshl_b32 s1, s1, 6
	s_lshr_b32 s21, s0, 5
	s_lshl_b32 s21, s21, 17
	s_add_u32 s1, s1, s21
	s_lshl_b32 s1, s1, 1
	s_add_u32 s1, s1, 0x4001000
	s_add_u32 s30, s68, s1
	s_addc_u32 s31, s69, 0
	s_movk_i32 s20, 0x800
	s_branch .Ltc2_d259

; __device__ __forceinline__ unsigned cvt_pk_bf16(float lo, float hi) { unsigned r; asm("v_cvt_pk_bf16_f32 %0, %1, %2" : "=v"(r) : "v"(lo), "v"(hi)); return r; }
; __device__ __forceinline__ void tconv_tile(LAS float* tile, const float* src, int ld, int k0, int n0, int mode, bf16_t* dst, int K) {
;     ...
;     for (int it = 0; it < 2; ++it) { const int idx = tid + it * 512, kk = idx >> 4, n4 = (idx & 15) * 4, nn = n0 + n4; int oc = nn; bool valid = true;
;         if (mode == 1) { if (nn < 7680) oc = nn; else if (nn < 18944) oc = nn + 48; else if (nn < INW) oc = 7680 + (nn - 18944); else valid = false; }
;         f32x4 v = (f32x4){0.f, 0.f, 0.f, 0.f}; if (valid) v = *(const f32x4*)(src + (size_t)(k0 + kk) * ld + oc);
;         tile[kk * 65 + n4 + 0] = v[0]; tile[kk * 65 + n4 + 1] = v[1]; tile[kk * 65 + n4 + 2] = v[2]; tile[kk * 65 + n4 + 3] = v[3]; }
;     __syncthreads();
;     { const int n = tid >> 3, k8 = (tid & 7) * 8; float v[8];
; #pragma unroll
;         for (int e = 0; e < 8; ++e) v[e] = tile[(k8 + e) * 65 + n];
;         u32x4 w; w.x = cvt_pk_bf16(v[0], v[1]); w.y = cvt_pk_bf16(v[2], v[3]); w.z = cvt_pk_bf16(v[4], v[5]); w.w = cvt_pk_bf16(v[6], v[7]);
;         *(u32x4*)(dst + (size_t)(n0 + n) * K + k0 + k8) = w; }
; __device__ __forceinline__ void prologue(LAS unsigned char* lds, const Ctx& P, int l) {
;     ...
;     for (int t = blockIdx.x; t < T_ALL; t += G) {
;         int q = t;
;         if (q < T_IN) { const int kt = q & 31, ntl = q >> 5; tconv_tile(tile, P.in[3] + (size_t)l * DM * INW, INW, kt * 64, ntl * 64, 1, (bf16_t*)(ws + WS_WIN), DM); continue; }
.Ltc2_d266:
	v_mov_b32_e32 v58, 0
	v_mov_b32_e32 v59, 0
	v_mov_b32_e32 v60, 0
	v_mov_b32_e32 v61, 0
	v_mov_b32_e32 v62, 0
	v_mov_b32_e32 v63, 0
	v_mov_b32_e32 v64, 0
	v_mov_b32_e32 v65, 0
	v_mul_u32_u24_e32 v26, s28, v20
	v_add_lshl_u32 v26, v26, v21, 2
	s_lshl_b32 s0, s28, 7
	v_add_u32_e32 v27, s0, v26
	v_cmp_gt_i32_e32 vcc, s29, v21
	s_and_saveexec_b64 s[0:1], vcc
	global_load_dwordx4 v[58:61], v26, s[26:27]
	global_load_dwordx4 v[62:65], v27, s[26:27]
	s_mov_b64 exec, s[0:1]
	s_add_u32 s24, s24, 0xe0
	s_cmpk_ge_u32 s25, 4480
	s_cbranch_scc1 .Ltc2_exit
	s_waitcnt vmcnt(15)
	v_add_u32_e32 v28, 0, v22
	ds_write2_b32 v28, v78, v79 offset1:1
	ds_write2_b32 v28, v80, v81 offset0:2 offset1:3
	v_add_u32_e32 v28, 0x2080, v28
	ds_write2_b32 v28, v82, v83 offset1:1
	ds_write2_b32 v28, v84, v85 offset0:2 offset1:3
	s_mov_b32 s21, s25
	s_mov_b32 s0, s21
	s_cmpk_lt_u32 s0, 9600
	s_cbranch_scc0 .Ltc2_c280
	s_and_b32 s1, s0, 31
	s_lshl_b32 s1, s1, 6
	s_lshr_b32 s21, s0, 5
	s_lshl_b32 s21, s21, 17
	s_add_u32 s1, s1, s21
	s_lshl_b32 s1, s1, 1
	s_add_u32 s1, s1, 0x4001000
	s_add_u32 s30, s68, s1
	s_addc_u32 s31, s69, 0
	s_movk_i32 s20, 0x800
	s_branch .Ltc2_d279

; __device__ __forceinline__ void tconv_tile(LAS float* tile, const float* src, int ld, int k0, int n0, int mode, bf16_t* dst, int K) {
;     ...
;     for (int it = 0; it < 2; ++it) { const int idx = tid + it * 512, kk = idx >> 4, n4 = (idx & 15) * 4, nn = n0 + n4; int oc = nn; bool valid = true;
;         if (mode == 1) { if (nn < 7680) oc = nn; else if (nn < 18944) oc = nn + 48; else if (nn < INW) oc = 7680 + (nn - 18944); else valid = false; }
; __device__ __forceinline__ void prologue(LAS unsigned char* lds, const Ctx& P, int l) {
;     ...
;         if (q < T_IN) { const int kt = q & 31, ntl = q >> 5; tconv_tile(tile, P.in[3] + (size_t)l * DM * INW, INW, kt * 64, ntl * 64, 1, (bf16_t*)(ws + WS_WIN), DM); continue; }
;         q -= T_IN;
;         if (q < T_BR) { const int br = q >> 9, r = q & 511, kt = r & 15, ntl = r >> 4;
;             tconv_tile(tile, P.in[23] + ((size_t)l * 4 + br) * DBR * DM, DM, kt * 64, ntl * 64, 0, (bf16_t*)(ws + WS_WBR) + (size_t)br * DM * DBR, DBR); continue; }
;         q -= T_BR;
;         if (q < T_OUT) { const int kt = q & 31, ntl = q >> 5; tconv_tile(tile, P.in[24] + (size_t)l * DM * DM, DM, kt * 64, ntl * 64, 0, (bf16_t*)(ws + WS_WOUT), DM); continue; }
.LBB0_868:
	v_mov_b32_e32 v26, 0x23f00
	ds_read_b64 v[34:35], v26 offset:24
	ds_read_b64 v[36:37], v26 offset:184
	ds_read_b64 v[38:39], v26 offset:192
	ds_read_b64 v[40:41], v26 offset:176
	ds_read_b64 v[42:43], v26 offset:136
	ds_read_b64 v[44:45], v26 offset:144
	ds_read_b64 v[46:47], v26 offset:80
	ds_read_b64 v[48:49], v26 offset:96
	s_waitcnt lgkmcnt(0)
	v_readfirstlane_b32 s4, v34
	v_readfirstlane_b32 s5, v35
	v_readfirstlane_b32 s6, v36
	v_readfirstlane_b32 s7, v37
	v_readfirstlane_b32 s8, v38
	v_readfirstlane_b32 s9, v39
	v_readfirstlane_b32 s10, v40
	v_readfirstlane_b32 s11, v41
	v_readfirstlane_b32 s12, v42
	v_readfirstlane_b32 s13, v43
	v_readfirstlane_b32 s14, v44
	v_readfirstlane_b32 s15, v45
	v_readfirstlane_b32 s16, v46
	v_readfirstlane_b32 s17, v47
	v_readfirstlane_b32 s18, v48
	v_readfirstlane_b32 s19, v49
	s_nop 3
	s_add_u32 s4, s4, 0x9460000
	s_addc_u32 s5, s5, 0
	s_add_u32 s6, s6, 0x2000000
	s_addc_u32 s7, s7, 0
	s_add_u32 s8, s8, 0x1000000
	s_addc_u32 s9, s9, 0
	s_add_u32 s10, s10, 0x1000000
	s_addc_u32 s11, s11, 0
	s_add_u32 s12, s12, 0x200000
	s_addc_u32 s13, s13, 0
	s_add_u32 s14, s14, 0x200000
	s_addc_u32 s15, s15, 0
	s_add_u32 s16, s16, 0x80000
	s_addc_u32 s17, s17, 0
	s_add_u32 s18, s18, 0x80000
	s_addc_u32 s19, s19, 0
	v_lshrrev_b32_e32 v20, 4, v234
	v_and_b32_e32 v21, 15, v234
	v_lshlrev_b32_e32 v21, 2, v21
	v_mul_u32_u24_e32 v22, 0x104, v20
	v_lshl_add_u32 v22, v21, 2, v22
	v_lshrrev_b32_e32 v24, 3, v234
	v_and_b32_e32 v25, 7, v234
	v_lshlrev_b32_e32 v25, 3, v25
	v_mul_u32_u24_e32 v23, 0x104, v25
	v_lshl_add_u32 v23, v24, 2, v23
	s_add_u32 s24, s2, 4352
	s_add_u32 s0, s24, 0x100
	s_cmpk_lt_u32 s24, 4480
	s_cselect_b32 s24, s0, s24
	s_mov_b32 s25, s24
	s_min_u32 s0, s24, 14015
	s_mov_b32 s21, s0
	s_mov_b32 s0, s21
	s_cmpk_lt_u32 s0, 9600
	s_cbranch_scc0 .Ltc1_c2
	s_and_b32 s1, s0, 31
	s_lshl_b32 s1, s1, 6
	s_lshr_b32 s21, s0, 5
	s_lshl_b32 s21, s21, 6
	s_movk_i32 s29, 64
	s_cmpk_lt_u32 s21, 7680
	s_cbranch_scc1 .Ltc1_n4
	s_cmpk_lt_u32 s21, 18944
	s_cbranch_scc0 .Ltc1_t3
	s_add_u32 s21, s21, 48
	s_branch .Ltc1_n4
